# attention K tile LDS image swizzled with (row & 15) instead of (row & 7): conflict-free ds_read_b128 under gfx950 lane groups (writers, DMA source permutation and reader addresses changed together)
# baseline (speedup 1.0000x reference)
; DI int v_st(int k, int c) { const int kk = (k & ~0xC) | ((k & 4) << 1) | ((k & 8) >> 1); return ((kk >> 3) * 4 + (c >> 5)) * 512 + ((kk & 7) * 32 + (c & 31)) * 2; }
; DI int v_rd_base(int lane) { return ((lane & 3) << 3) | (((lane >> 2) & 3) << 6) | (((lane >> 4) & 1) << 5) | (((lane >> 5) & 1) << 8); }
; #define SLOAD(i, k0) do { sr_[i].vs0 = *(const bf16x8*)(&Vh[(long)((k0) + sr) * LDA_ + sc]); sr_[i].vs1 = *(const bf16x8*)(&Vh[(long)((k0) + 32 + sr) * LDA_ + sc]); \
;     sr_[i].ks0 = *(const bf16x8*)(&Kh[(long)((k0) + sr) * LDA_ + sc]); sr_[i].ks1 = *(const bf16x8*)(&Kh[(long)((k0) + 32 + sr) * LDA_ + sc]); } while (0)
; #define SWRITE(b, i) do { *(bf16x8*)(V_lds + (b) * SHM_V + vst0) = sr_[i].vs0;          \
;     *(bf16x8*)(V_lds + (b) * SHM_V + vst1) = sr_[i].vs1; int kc = sc * 2;               \
;     *(bf16x8*)(K_lds + (b) * SHM_K + KSWZ(sr, kc)) = sr_[i].ks0;                       \
;     *(bf16x8*)(K_lds + (b) * SHM_K + KSWZ(32 + sr, kc)) = sr_[i].ks1; } while (0)
; DI void attn_unit(const bf16_t* __restrict__ Qb, const bf16_t* __restrict__ Kh, const bf16_t* __restrict__ Vh, bf16_t* __restrict__ Ob, const float* __restrict__ onw, int seq, char* lds) {
;     int tid_ = threadIdx.x; asm volatile("" : "+v"(tid_));
;     const int tid = tid_, wid = tid >> 6, lane = tid & 63, r32 = lane & 31, hi = lane >> 5;
;     char* V_lds = lds; char* K_lds = lds + 2 * SHM_V;
;     float* wsf = (float*)(lds + 2 * SHM_V + 2 * SHM_K) + wid * 64; float* li_l = wsf; float* al_l = wsf + 32;
;     float m_reg = 0.f, l_reg = 0; f32x16 o[4]; bf16x8 qr[8];
; #pragma unroll
;     for (int d = 0; d < 4; ++d)
; #pragma unroll
;         for (int i = 0; i < 16; ++i) o[d][i] = 0.f;
;     const bf16_t* Qw = Qb + (long)((wid & 3) * 32 + r32) * LDA_ + (wid >> 2) * 128 + hi * 8;
; #pragma unroll
;     for (int d0 = 0; d0 < 8; ++d0) qr[d0] = *(const bf16x8*)(Qw + d0 * 16);
;     const int sr = tid >> 4, sc = (tid & 15) * 8, vst0 = v_st(sr, sc), vst1 = v_st(32 + sr, sc);
;     const int vb0 = (int)(uintptr_t)V_lds + v_rd_base(lane);
;     struct { bf16x8 vs0, vs1, ks0, ks1; } sr_[1];
;     ...
;     f32x16 pA0, pA1, pB0, pB1; float alA, alB; bf16x8 pa0, pa1, pa2, pa3; const int NT = seq / 64;
;     constexpr int SE = 0, SO = 0;
;     SLOAD(SE, 0); asm volatile("s_waitcnt vmcnt(0)" ::: "memory"); SWRITE(0, SE); __syncthreads();
.LBB0_579:
	s_and_b32 s12, s14, 1
	s_lshl_b32 s2, s15, 7
	s_add_u32 s2, s68, s2
	s_addc_u32 s3, s69, 0
	s_lshl_b64 s[66:67], s[2:3], 10
	s_lshl_b64 s[2:3], s[2:3], 11
	s_add_u32 s2, s30, s2
	s_addc_u32 s3, s31, s3
	s_lshl_b32 s72, s12, 8
	s_lshl_b32 s12, s12, 9
	s_add_u32 s2, s2, s12
	s_waitcnt vmcnt(0)
	v_mov_b32_e32 v80, v192
	s_addc_u32 s3, s3, 0
	s_lshl_b64 s[14:15], s[68:69], 11
	s_add_u32 s12, s30, s14
	v_ashrrev_i32_e32 v48, 4, v80
	v_lshlrev_b32_e32 v20, 3, v80
	v_add_u32_e32 v16, 32, v48
	s_addc_u32 s15, s31, s15
	v_and_b32_e32 v0, 0x78, v20
	v_ashrrev_i32_e32 v49, 31, v48
	v_ashrrev_i32_e32 v17, 31, v16
	s_add_u32 s14, s12, s72
	v_lshlrev_b32_e32 v21, 1, v0
	v_lshlrev_b64 v[0:1], 11, v[48:49]
	v_lshlrev_b64 v[4:5], 11, v[16:17]
	s_addc_u32 s15, s15, 0
	v_or_b32_e32 v0, v0, v21
	v_or_b32_e32 v4, v4, v21
	v_lshl_add_u64 v[50:51], s[14:15], 0, v[0:1]
	v_lshl_add_u64 v[12:13], s[14:15], 0, v[4:5]
	s_add_u32 s98, s14, 0x20400
	s_addc_u32 s99, s15, 0
	v_readfirstlane_b32 s100, v80
	v_and_b32_e32 v250, 63, v80
	v_lshrrev_b32_e32 v251, 6, v80
	v_lshrrev_b32_e32 v252, 4, v250
	v_and_b32_e32 v253, 3, v251
	v_lshl_add_u32 v253, v253, 2, v252
	v_and_b32_e32 v246, 15, v250
	v_xor_b32_e32 v246, v246, v253
	v_lshlrev_b32_e32 v246, 4, v246
	v_lshl_add_u32 v252, v251, 2, v252
	v_lshl_add_u32 v246, v252, 11, v246
	v_add_u32_e32 v246, 0x20000, v246
	v_add_u32_e32 v247, 0x10000, v246
	v_bfe_u32 v252, v250, 2, 3
	v_and_b32_e32 v253, 3, v252
	v_lshrrev_b32_e32 v252, 2, v252
	v_lshl_add_u32 v253, v252, 3, v253
	v_bfe_u32 v252, v251, 1, 1
	v_lshl_add_u32 v253, v252, 2, v253
	v_bfe_u32 v252, v251, 2, 1
	v_lshl_add_u32 v253, v252, 4, v253
	v_lshlrev_b32_e32 v248, 11, v253
	v_and_b32_e32 v252, 1, v251
	v_lshlrev_b32_e32 v252, 1, v252
	v_lshrrev_b32_e32 v253, 5, v250
	v_add_u32_e32 v252, v252, v253
	v_and_b32_e32 v253, 3, v250
	v_lshl_add_u32 v252, v252, 2, v253
	v_lshl_add_u32 v248, v252, 4, v248
	v_add_u32_e32 v248, 0x200, v248
	v_add_u32_e32 v249, 0x10000, v248
	s_lshl_b32 s100, s100, 4
	v_and_b32_e32 v252, 8, v80
	v_lshlrev_b32_e32 v252, 4, v252
	v_and_b32_e32 v253, 0x80, v80
	global_load_dwordx4 v[0:3], v[50:51], off offset:1536
	global_load_dwordx4 v[4:7], v[12:13], off offset:1536
	global_load_dwordx4 v[8:11], v[50:51], off offset:1024
	s_nop 0
	global_load_dwordx4 v[12:15], v[12:13], off offset:1024
	v_lshrrev_b32_e32 v17, 1, v80
	v_and_b32_e32 v155, 31, v80
	v_and_b32_e32 v170, 0x60, v17
	v_or_b32_e32 v17, v170, v155
	v_lshlrev_b32_e32 v184, 11, v17
	v_ashrrev_i32_e32 v17, 1, v80
	v_and_b32_e32 v148, 0xffffff80, v17
	v_bfe_u32 v151, v80, 5, 1
	v_lshl_add_u64 v[18:19], s[2:3], 0, v[184:185]
	v_ashrrev_i32_e32 v149, 31, v148
	v_lshl_add_u64 v[18:19], v[148:149], 1, v[18:19]
	v_lshlrev_b32_e32 v184, 4, v151
	v_lshl_add_u64 v[18:19], v[18:19], 0, v[184:185]
	global_load_dwordx4 v[140:143], v[18:19], off
	global_load_dwordx4 v[136:139], v[18:19], off offset:32
	global_load_dwordx4 v[132:135], v[18:19], off offset:64
	global_load_dwordx4 v[128:131], v[18:19], off offset:96
	global_load_dwordx4 v[124:127], v[18:19], off offset:128
	global_load_dwordx4 v[120:123], v[18:19], off offset:160
	global_load_dwordx4 v[116:119], v[18:19], off offset:192
	global_load_dwordx4 v[112:115], v[18:19], off offset:224
	v_and_b32_e32 v22, 0xfffff0, v48
	v_lshlrev_b32_e32 v23, 1, v48
	v_lshrrev_b32_e32 v24, 1, v48
	v_and_b32_e32 v25, 3, v48
	v_and_or_b32 v22, v23, 8, v22
	v_and_or_b32 v23, v24, 4, v25
	v_and_b32_e32 v24, 0xfffff0, v16
	v_lshlrev_b32_e32 v25, 1, v16
	v_and_b32_e32 v17, 0x70, v80
	v_bfe_u32 v20, v20, 5, 2
	v_lshlrev_b32_e32 v26, 8, v48
	v_lshlrev_b32_e32 v16, 8, v16
	v_lshrrev_b32_e32 v22, 1, v22
	v_and_or_b32 v24, v25, 8, v24
	v_and_b32_e32 v27, 48, v21
	v_bitop3_b32 v25, v21, v26, v17 bitop3:0xde
	v_bitop3_b32 v16, v21, v16, v17 bitop3:0xde
	v_or_b32_e32 v17, v22, v20
	v_lshrrev_b32_e32 v21, 1, v24
	v_lshlrev_b32_e32 v23, 6, v23
	v_add_u32_e32 v205, 0, v16
	v_xor_b32_e32 v205, v253, v205
	v_lshlrev_b32_e32 v16, 9, v17
	v_or_b32_e32 v17, v21, v20
	v_or3_b32 v16, v16, v23, v27
	v_lshlrev_b32_e32 v17, 9, v17
	v_lshlrev_b32_e32 v66, 4, v80
	v_or3_b32 v17, v17, v23, v27
	v_add_u32_e32 v206, 0, v16
	v_add_u32_e32 v204, 0, v25
	v_xor_b32_e32 v204, v253, v204
	v_add_u32_e32 v207, 0, v17
	s_waitcnt vmcnt(0)
	s_mov_b64 s[2:3], 0x20000
	v_and_b32_e32 v81, 63, v80
	s_mov_b32 s12, s13
	s_mov_b32 s14, s13
	s_mov_b32 s15, s13
	s_mov_b32 s16, s13
	s_mov_b32 s17, s13
	s_mov_b32 s18, s13
	s_mov_b32 s19, s13
	s_mov_b32 s20, s13
	s_mov_b32 s21, s13
	s_mov_b32 s22, s13
	s_waitcnt vmcnt(11)
	ds_write_b128 v206, v[0:3]
	s_waitcnt vmcnt(10)
	ds_write_b128 v207, v[4:7]
	s_waitcnt vmcnt(9)
	ds_write_b128 v204, v[8:11] offset:32768
	s_waitcnt vmcnt(8)
	ds_write_b128 v205, v[12:15] offset:32768
	v_lshlrev_b32_e32 v12, 8, v155
	v_and_b32_e32 v13, 0x70, v66
	v_bitop3_b32 v0, v184, v12, v13 bitop3:0xde
	v_add_u32_e32 v183, 0, v0
	v_xor_b32_e32 v183, v252, v183
	s_waitcnt lgkmcnt(0)
	s_barrier
; #define MFMA32(a, b, c) __builtin_amdgcn_mfma_f32_32x32x16_bf16((a), (b), (c), 0, 0, 0)
; #define SLOAD(i, k0) do { sr_[i].vs0 = *(const bf16x8*)(&Vh[(long)((k0) + sr) * LDA_ + sc]); sr_[i].vs1 = *(const bf16x8*)(&Vh[(long)((k0) + 32 + sr) * LDA_ + sc]); \
;     sr_[i].ks0 = *(const bf16x8*)(&Kh[(long)((k0) + sr) * LDA_ + sc]); sr_[i].ks1 = *(const bf16x8*)(&Kh[(long)((k0) + 32 + sr) * LDA_ + sc]); } while (0)
; #define SWRITE(b, i) do { *(bf16x8*)(V_lds + (b) * SHM_V + vst0) = sr_[i].vs0;          \
;     *(bf16x8*)(V_lds + (b) * SHM_V + vst1) = sr_[i].vs1; int kc = sc * 2;               \
;     *(bf16x8*)(K_lds + (b) * SHM_K + KSWZ(sr, kc)) = sr_[i].ks0;                       \
;     *(bf16x8*)(K_lds + (b) * SHM_K + KSWZ(32 + sr, kc)) = sr_[i].ks1; } while (0)
; #define SWAIT() asm volatile("s_waitcnt vmcnt(0)" ::: "memory")
; DI void qkt(f32x16& p0, f32x16& p1, const char* Ks, const bf16x8* qr, float negm, int r32, int hi) {
; #pragma unroll
;     for (int i = 0; i < 16; ++i) { p0[i] = negm; p1[i] = negm; }
; #pragma unroll
;     for (int d0 = 0; d0 < 8; ++d0) { const int cb = (d0 * 16 + hi * 8) * 2;
;         bf16x8 b0 = *(const bf16x8*)(Ks + KSWZ(r32, cb));
;         bf16x8 b1 = *(const bf16x8*)(Ks + KSWZ(32 + r32, cb));
;         p0 = MFMA32(b0, qr[d0], p0);
;         p1 = MFMA32(b1, qr[d0], p1); }
; }
; DI void attn_unit(const bf16_t* __restrict__ Qb, const bf16_t* __restrict__ Kh, const bf16_t* __restrict__ Vh, bf16_t* __restrict__ Ob, const float* __restrict__ onw, int seq, char* lds) {
;     ...
;     qkt(pA0, pA1, K_lds, qr, 0.f, r32, hi); partialSM<true>(pA0, pA1, m_reg, alA);
;     SLOAD(SO, 64);
;     SWAIT(); SWRITE(1, SO); __syncthreads();
	ds_read_b128 v[0:3], v183 offset:32768
	ds_read_b128 v[4:7], v183 offset:40960
	s_waitcnt vmcnt(7) lgkmcnt(1)
	v_mfma_f32_32x32x16_bf16 v[32:47], v[0:3], v[140:143], 0
	v_or_b32_e32 v0, 32, v184
	v_bitop3_b32 v0, v0, v12, v13 bitop3:0xde
	v_add_u32_e32 v208, 0, v0
	v_xor_b32_e32 v208, v252, v208
	v_lshl_add_u64 v[8:9], v[50:51], 0, s[2:3]
	v_lshl_add_u64 v[10:11], v[50:51], 0, s[56:57]
	s_add_i32 s2, 0, 0x10000
	s_cmp_lg_u32 0, -1
	s_waitcnt lgkmcnt(0)
	v_mfma_f32_32x32x16_bf16 v[16:31], v[4:7], v[140:143], 0
	ds_read_b128 v[0:3], v208 offset:32768
	ds_read_b128 v[4:7], v208 offset:40960
	s_mov_b32 s23, s13
	s_mov_b32 s24, s13
	s_mov_b32 s25, s13
	s_mov_b32 s26, s13
	s_mov_b32 s27, s13
	s_cselect_b32 s43, 0, 0
	s_waitcnt vmcnt(6) lgkmcnt(1)
	v_mfma_f32_32x32x16_bf16 v[32:47], v[0:3], v[136:139], v[32:47]
	v_or_b32_e32 v0, 64, v184
	v_bitop3_b32 v0, v0, v12, v13 bitop3:0xde
	v_add_u32_e32 v209, 0, v0
	v_xor_b32_e32 v209, v252, v209
	s_mov_b32 s42, 2
	v_mov_b32_e32 v173, 0
	s_waitcnt lgkmcnt(0)
	v_mfma_f32_32x32x16_bf16 v[16:31], v[4:7], v[136:139], v[16:31]
	ds_read_b128 v[0:3], v209 offset:32768
	ds_read_b128 v[4:7], v209 offset:40960
	s_waitcnt vmcnt(5) lgkmcnt(1)
	v_mfma_f32_32x32x16_bf16 v[32:47], v[0:3], v[132:135], v[32:47]
	v_or_b32_e32 v0, 0x60, v184
	v_bitop3_b32 v0, v0, v12, v13 bitop3:0xde
	v_add_u32_e32 v210, 0, v0
	v_xor_b32_e32 v210, v252, v210
	s_waitcnt lgkmcnt(0)
	v_mfma_f32_32x32x16_bf16 v[16:31], v[4:7], v[132:135], v[16:31]
	ds_read_b128 v[0:3], v210 offset:32768
	ds_read_b128 v[4:7], v210 offset:40960
	s_waitcnt vmcnt(4) lgkmcnt(1)
	v_mfma_f32_32x32x16_bf16 v[32:47], v[0:3], v[128:131], v[32:47]
	v_or_b32_e32 v0, 0x80, v184
	v_bitop3_b32 v0, v0, v12, v13 bitop3:0xde
	v_add_u32_e32 v211, 0, v0
	v_xor_b32_e32 v211, v252, v211
	ds_read_b128 v[0:3], v211 offset:32768
	s_waitcnt lgkmcnt(1)
	v_mfma_f32_32x32x16_bf16 v[16:31], v[4:7], v[128:131], v[16:31]
	ds_read_b128 v[4:7], v211 offset:40960
	global_load_dwordx4 v[50:53], v[8:9], off offset:1536
	global_load_dwordx4 v[54:57], v[10:11], off offset:1536
	global_load_dwordx4 v[58:61], v[8:9], off offset:1024
	global_load_dwordx4 v[62:65], v[10:11], off offset:1024
	v_lshlrev_b32_e32 v8, 3, v81
	v_lshlrev_b32_e32 v10, 1, v80
	s_waitcnt vmcnt(7) lgkmcnt(1)
	v_mfma_f32_32x32x16_bf16 v[32:47], v[0:3], v[124:127], v[32:47]
	v_or_b32_e32 v0, 0xa0, v184
	v_bitop3_b32 v0, v0, v12, v13 bitop3:0xde
	v_add_u32_e32 v212, 0, v0
	v_xor_b32_e32 v212, v252, v212
	ds_read_b128 v[0:3], v212 offset:32768
	s_waitcnt lgkmcnt(1)
	v_mfma_f32_32x32x16_bf16 v[16:31], v[4:7], v[124:127], v[16:31]
	v_and_b32_e32 v4, 0x3fffffc0, v80
	v_lshl_add_u32 v171, v4, 2, s2
	ds_read_b128 v[4:7], v212 offset:40960
	v_cmp_gt_u32_e64 s[2:3], 32, v81
	v_lshl_add_u32 v172, v155, 2, v171
	s_waitcnt vmcnt(6) lgkmcnt(1)
	v_mfma_f32_32x32x16_bf16 v[32:47], v[0:3], v[120:123], v[32:47]
	v_and_b32_e32 v0, 0xc0, v66
	v_and_or_b32 v9, v8, 24, v0
	v_or_b32_e32 v0, 0xc0, v184
	v_bitop3_b32 v0, v0, v12, v13 bitop3:0xde
	v_add_u32_e32 v213, 0, v0
	v_xor_b32_e32 v213, v252, v213
	ds_read_b128 v[0:3], v213 offset:32768
	s_waitcnt lgkmcnt(1)
	v_mfma_f32_32x32x16_bf16 v[16:31], v[4:7], v[120:123], v[16:31]
	v_and_b32_e32 v4, 32, v10
	v_and_b32_e32 v5, 0x100, v8
	v_or3_b32 v82, v9, v4, v5
	ds_read_b128 v[4:7], v213 offset:40960
	v_add_u32_e32 v175, s43, v82
	s_addk_i32 s43, 0x4000
	v_add_u32_e32 v174, s43, v82
	s_waitcnt vmcnt(5) lgkmcnt(1)
	v_mfma_f32_32x32x16_bf16 v[32:47], v[0:3], v[116:119], v[32:47]
	v_or_b32_e32 v0, 0xe0, v184
	v_bitop3_b32 v0, v0, v12, v13 bitop3:0xde
	v_add_u32_e32 v214, 0, v0
	v_xor_b32_e32 v214, v252, v214
	ds_read_b128 v[0:3], v214 offset:32768
	ds_read_b128 v[66:69], v214 offset:40960
	s_waitcnt vmcnt(0)
	s_waitcnt vmcnt(3)
	ds_write_b128 v206, v[50:53] offset:16384
	s_waitcnt vmcnt(2)
	ds_write_b128 v207, v[54:57] offset:16384
	s_waitcnt vmcnt(1)
	ds_write_b128 v204, v[58:61] offset:49152
	s_waitcnt vmcnt(0)
	ds_write_b128 v205, v[62:65] offset:49152
	s_waitcnt lgkmcnt(6)
	v_mfma_f32_32x32x16_bf16 v[16:31], v[4:7], v[116:119], v[16:31]
	s_waitcnt lgkmcnt(0)
	s_barrier
; DI float smA_max0(const f32x16& p0) {
;     float mx = p0[0];
; #pragma unroll
;     for (int r = 1; r < 16; ++r) mx = fmaxf(mx, p0[r]);
;     return mx;
; }
; DI float smA_max1(float mx, const f32x16& p1) {
; #pragma unroll
;     for (int r = 0; r < 16; ++r) mx = fmaxf(mx, p1[r]);
;     auto rr = __builtin_amdgcn_permlane32_swap(__float_as_uint(mx), __float_as_uint(mx), false, false);
;     return fmaxf(__uint_as_float(rr[0]), __uint_as_float(rr[1]));
; }
; template <int LO> DI void smA_exp(f32x16& p0) {
; #pragma unroll
;     for (int r = LO; r < LO + 8; ++r) p0[r] = __builtin_amdgcn_exp2f(p0[r]);
; }
; template <bool FIRST> DI void smB(f32x16& p0, f32x16& p1, float pmax, float& m_reg, float& alpha) {
;     if (!FIRST && __builtin_expect(__all(pmax <= ATHR2), 1)) { alpha = 1.f; }
;     else {
;         const float delta = FIRST ? pmax : fmaxf(pmax, 0.f);
;         alpha = __builtin_amdgcn_exp2f(-delta); m_reg += delta;
; #pragma unroll
;         for (int r = 0; r < 16; ++r) { p0[r] *= alpha; p1[r] -= delta; }
;     }
; }
; template <bool FIRST> DI void partialSM(f32x16& p0, f32x16& p1, float& m_reg, float& alpha) {
;     const float pmax = smA_max1(smA_max0(p0), p1);
;     smA_exp<0>(p0); smA_exp<8>(p0);
;     smB<FIRST>(p0, p1, pmax, m_reg, alpha);
; }
; DI void attn_unit(const bf16_t* __restrict__ Qb, const bf16_t* __restrict__ Kh, const bf16_t* __restrict__ Vh, bf16_t* __restrict__ Ob, const float* __restrict__ onw, int seq, char* lds) {
;     ...
;     float m_reg = 0.f, l_reg = 0; f32x16 o[4]; bf16x8 qr[8];
; #pragma unroll
;     for (int d = 0; d < 4; ++d)
; #pragma unroll
;         for (int i = 0; i < 16; ++i) o[d][i] = 0.f;
	v_mfma_f32_32x32x16_bf16 v[32:47], v[0:3], v[112:115], v[32:47]
	v_mov_b64_e32 v[0:1], s[12:13]
	v_mov_b64_e32 v[14:15], s[26:27]
	v_mov_b64_e32 v[2:3], s[14:15]
	v_mov_b64_e32 v[4:5], s[16:17]
	v_mov_b64_e32 v[6:7], s[18:19]
	v_mov_b64_e32 v[8:9], s[20:21]
	v_mov_b64_e32 v[10:11], s[22:23]
	v_mfma_f32_32x32x16_bf16 v[16:31], v[66:69], v[112:115], v[16:31]
	s_nop 3
	v_max_f32_e32 v66, v33, v33
	v_max_f32_e32 v67, v32, v32
	v_max_f32_e32 v66, v67, v66
	v_max3_f32 v66, v66, v34, v35
	v_max3_f32 v66, v66, v36, v37
	v_max3_f32 v66, v66, v38, v39
	v_max3_f32 v66, v66, v40, v41
	v_max3_f32 v66, v66, v42, v43
	v_max3_f32 v66, v66, v44, v45
	v_max3_f32 v66, v66, v46, v47
	v_max3_f32 v66, v66, v16, v17
	v_max3_f32 v66, v66, v18, v19
	v_max3_f32 v66, v66, v20, v21
	v_max3_f32 v66, v66, v22, v23
	v_max3_f32 v66, v66, v24, v25
	v_max3_f32 v66, v66, v26, v27
	v_max3_f32 v66, v66, v28, v29
	v_max3_f32 v66, v66, v30, v31
	v_mov_b32_e32 v67, v66
	s_nop 1
	v_permlane32_swap_b32_e32 v66, v67
	v_max_f32_e32 v50, v67, v67
	v_max_f32_e32 v51, v66, v66
	v_max_f32_e32 v50, v51, v50
	v_exp_f32_e32 v32, v32
	v_exp_f32_e64 v150, -v50
	v_exp_f32_e32 v33, v33
	v_exp_f32_e32 v34, v34
	v_exp_f32_e32 v35, v35
	v_exp_f32_e32 v36, v36
	v_exp_f32_e32 v37, v37
	v_exp_f32_e32 v38, v38
	v_exp_f32_e32 v39, v39
	v_exp_f32_e32 v40, v40
	v_exp_f32_e32 v42, v42
	v_exp_f32_e32 v44, v44
	v_exp_f32_e32 v46, v46
	v_exp_f32_e32 v47, v47
	v_exp_f32_e32 v45, v45
	v_exp_f32_e32 v43, v43
	v_exp_f32_e32 v41, v41
	v_sub_f32_e32 v66, v18, v50
	v_sub_f32_e32 v65, v17, v50
	v_sub_f32_e32 v64, v16, v50
	v_lshl_add_u64 v[16:17], s[68:69], 0, v[48:49]
	v_and_b32_e32 v18, 15, v80
	v_lshlrev_b64 v[16:17], 11, v[16:17]
	v_lshlrev_b32_e32 v18, 4, v18
	v_or3_b32 v16, v16, s72, v18
	v_mov_b64_e32 v[12:13], s[24:25]
	v_pk_mul_f32 v[146:147], v[46:47], v[150:151] op_sel_hi:[1,0]
	v_pk_mul_f32 v[160:161], v[44:45], v[150:151] op_sel_hi:[1,0]
	v_pk_mul_f32 v[164:165], v[42:43], v[150:151] op_sel_hi:[1,0]
	v_pk_mul_f32 v[168:169], v[40:41], v[150:151] op_sel_hi:[1,0]
	v_pk_mul_f32 v[156:157], v[38:39], v[150:151] op_sel_hi:[1,0]
	v_pk_mul_f32 v[158:159], v[36:37], v[150:151] op_sel_hi:[1,0]
	v_pk_mul_f32 v[162:163], v[34:35], v[150:151] op_sel_hi:[1,0]
	v_pk_mul_f32 v[166:167], v[32:33], v[150:151] op_sel_hi:[1,0]
	v_sub_f32_e32 v79, v31, v50
	v_sub_f32_e32 v78, v30, v50
	v_sub_f32_e32 v77, v29, v50
	v_sub_f32_e32 v76, v28, v50
	v_sub_f32_e32 v75, v27, v50
	v_sub_f32_e32 v74, v26, v50
	v_sub_f32_e32 v73, v25, v50
	v_sub_f32_e32 v72, v24, v50
	v_sub_f32_e32 v71, v23, v50
	v_sub_f32_e32 v70, v22, v50
	v_sub_f32_e32 v69, v21, v50
	v_sub_f32_e32 v68, v20, v50
	v_sub_f32_e32 v67, v19, v50
	v_add_f32_e32 v215, 0, v50
	v_lshl_add_u64 v[152:153], s[40:41], 0, v[16:17]
	v_mov_b64_e32 v[62:63], v[14:15]
	v_mov_b64_e32 v[30:31], v[14:15]
	v_mov_b64_e32 v[46:47], v[14:15]
	v_mov_b64_e32 v[60:61], v[12:13]
	v_mov_b64_e32 v[58:59], v[10:11]
	v_mov_b64_e32 v[56:57], v[8:9]
	v_mov_b64_e32 v[54:55], v[6:7]
	v_mov_b64_e32 v[52:53], v[4:5]
	v_mov_b64_e32 v[50:51], v[2:3]
	v_mov_b64_e32 v[48:49], v[0:1]
	v_mov_b64_e32 v[28:29], v[12:13]
	v_mov_b64_e32 v[26:27], v[10:11]
	v_mov_b64_e32 v[24:25], v[8:9]
	v_mov_b64_e32 v[22:23], v[6:7]
	v_mov_b64_e32 v[20:21], v[4:5]
	v_mov_b64_e32 v[18:19], v[2:3]
	v_mov_b64_e32 v[16:17], v[0:1]
	v_mov_b64_e32 v[44:45], v[12:13]
	v_mov_b64_e32 v[42:43], v[10:11]
	v_mov_b64_e32 v[40:41], v[8:9]
	v_mov_b64_e32 v[38:39], v[6:7]
	v_mov_b64_e32 v[36:37], v[4:5]
	v_mov_b64_e32 v[34:35], v[2:3]
	v_mov_b64_e32 v[32:33], v[0:1]
